# GEMM1 main K-loop LDS-DMA loads in SGPR-base+VGPR-offset form (no per-lane 64-bit address adds), on top of the barrier invalidate hoists
# baseline (speedup 1.0000x reference)
.LBB0_233:
	s_add_u32 s6, s2, 0xfffc0080
	s_addc_u32 s7, s3, -1
	s_add_i32 s68, 0, 0x10000
	s_cmp_eq_u32 s67, 12
	s_cselect_b32 s9, s35, s7
	s_cselect_b32 s8, s41, s6
	v_add_u32_e32 v136, s68, v168
	s_cselect_b32 s7, s31, s66
	s_cselect_b32 s6, s64, s65
	s_add_i32 s70, 0, 0x14000
	ds_read_b128 v[128:131], v136
	ds_read_b128 v[132:135], v136 offset:1024
	ds_read_b128 v[152:155], v136 offset:2048
	ds_read_b128 v[156:159], v136 offset:3072
	v_add_u32_e32 v136, s70, v168
	ds_read_b128 v[160:163], v136
	ds_read_b128 v[170:173], v136 offset:1024
	ds_read_b128 v[194:197], v136 offset:2048
	ds_read_b128 v[198:201], v136 offset:3072
	s_add_i32 m0, s48, 0xc000
	ds_read_b128 v[202:205], v169
	ds_read_b128 v[206:209], v169 offset:1024
	ds_read_b128 v[210:213], v169 offset:2048
	ds_read_b128 v[214:217], v169 offset:3072
	ds_read_b128 v[218:221], v169 offset:4096
	ds_read_b128 v[222:225], v169 offset:5120
	ds_read_b128 v[226:229], v169 offset:6144
	ds_read_b128 v[230:233], v169 offset:7168
	global_load_lds_dwordx4 v148, s[2:3]
	s_add_i32 m0, s48, 0xe000
	s_nop 0
	global_load_lds_dwordx4 v150, s[2:3]
	s_waitcnt vmcnt(8)
	s_waitcnt lgkmcnt(0)
	s_barrier
	s_setprio 1
	s_waitcnt lgkmcnt(0)
	v_mfma_f32_16x16x32_bf16 v[124:127], v[128:131], v[202:205], v[124:127]
	v_mfma_f32_16x16x32_bf16 v[120:123], v[152:155], v[202:205], v[120:123]
	v_mfma_f32_16x16x32_bf16 v[108:111], v[128:131], v[210:213], v[108:111]
	v_mfma_f32_16x16x32_bf16 v[104:107], v[152:155], v[210:213], v[104:107]
	v_mfma_f32_16x16x32_bf16 v[92:95], v[128:131], v[218:221], v[92:95]
	v_mfma_f32_16x16x32_bf16 v[88:91], v[152:155], v[218:221], v[88:91]
	v_mfma_f32_16x16x32_bf16 v[76:79], v[128:131], v[226:229], v[76:79]
	v_mfma_f32_16x16x32_bf16 v[72:75], v[152:155], v[226:229], v[72:75]
	v_mfma_f32_16x16x32_bf16 v[124:127], v[132:135], v[206:209], v[124:127]
	v_mfma_f32_16x16x32_bf16 v[120:123], v[156:159], v[206:209], v[120:123]
	v_mfma_f32_16x16x32_bf16 v[108:111], v[132:135], v[214:217], v[108:111]
	v_mfma_f32_16x16x32_bf16 v[104:107], v[156:159], v[214:217], v[104:107]
	v_mfma_f32_16x16x32_bf16 v[92:95], v[132:135], v[222:225], v[92:95]
	v_mfma_f32_16x16x32_bf16 v[88:91], v[156:159], v[222:225], v[88:91]
	v_mfma_f32_16x16x32_bf16 v[76:79], v[132:135], v[230:233], v[76:79]
	v_mfma_f32_16x16x32_bf16 v[72:75], v[156:159], v[230:233], v[72:75]
	s_setprio 0
	s_setprio 1
	v_mfma_f32_16x16x32_bf16 v[116:119], v[160:163], v[202:205], v[116:119]
	v_mfma_f32_16x16x32_bf16 v[112:115], v[194:197], v[202:205], v[112:115]
	v_mfma_f32_16x16x32_bf16 v[100:103], v[160:163], v[210:213], v[100:103]
	v_mfma_f32_16x16x32_bf16 v[96:99], v[194:197], v[210:213], v[96:99]
	v_mfma_f32_16x16x32_bf16 v[84:87], v[160:163], v[218:221], v[84:87]
	v_mfma_f32_16x16x32_bf16 v[80:83], v[194:197], v[218:221], v[80:83]
	v_mfma_f32_16x16x32_bf16 v[68:71], v[160:163], v[226:229], v[68:71]
	v_mfma_f32_16x16x32_bf16 v[64:67], v[194:197], v[226:229], v[64:67]
	v_mfma_f32_16x16x32_bf16 v[116:119], v[170:173], v[206:209], v[116:119]
	v_mfma_f32_16x16x32_bf16 v[112:115], v[198:201], v[206:209], v[112:115]
	v_mfma_f32_16x16x32_bf16 v[100:103], v[170:173], v[214:217], v[100:103]
	v_mfma_f32_16x16x32_bf16 v[96:99], v[198:201], v[214:217], v[96:99]
	v_mfma_f32_16x16x32_bf16 v[84:87], v[170:173], v[222:225], v[84:87]
	v_mfma_f32_16x16x32_bf16 v[80:83], v[198:201], v[222:225], v[80:83]
	v_mfma_f32_16x16x32_bf16 v[68:71], v[170:173], v[230:233], v[68:71]
	v_mfma_f32_16x16x32_bf16 v[64:67], v[198:201], v[230:233], v[64:67]
	s_setprio 0
	s_barrier
	s_add_i32 s68, s68, s47
	s_mov_b32 m0, s68
	ds_read_b128 v[202:205], v169 offset:16384
	ds_read_b128 v[206:209], v169 offset:17408
	ds_read_b128 v[210:213], v169 offset:18432
	ds_read_b128 v[214:217], v169 offset:19456
	ds_read_b128 v[218:221], v169 offset:20480
	ds_read_b128 v[222:225], v169 offset:21504
	ds_read_b128 v[226:229], v169 offset:22528
	ds_read_b128 v[230:233], v169 offset:23552
	global_load_lds_dwordx4 v144, s[6:7]
	s_add_i32 m0, s68, 0x2000
	s_add_u32 s68, s6, 0x40000
	s_addc_u32 s69, s7, 0
	s_add_i32 s70, s70, s47
	global_load_lds_dwordx4 v140, s[6:7]
	s_mov_b32 m0, s70
	s_nop 0
	global_load_lds_dwordx4 v144, s[68:69]
	s_add_i32 m0, s70, 0x2000
	s_nop 0
	global_load_lds_dwordx4 v140, s[68:69]
	s_mov_b32 m0, s48
	s_nop 0
	global_load_lds_dwordx4 v146, s[8:9]
	s_mov_b32 m0, s49
	s_nop 0
	global_load_lds_dwordx4 v142, s[8:9]
	s_waitcnt vmcnt(8)
	s_waitcnt lgkmcnt(0)
	s_barrier
	s_setprio 1
	s_waitcnt lgkmcnt(0)
	v_mfma_f32_16x16x32_bf16 v[60:63], v[128:131], v[202:205], v[60:63]
	v_mfma_f32_16x16x32_bf16 v[56:59], v[152:155], v[202:205], v[56:59]
	v_mfma_f32_16x16x32_bf16 v[44:47], v[128:131], v[210:213], v[44:47]
	v_mfma_f32_16x16x32_bf16 v[40:43], v[152:155], v[210:213], v[40:43]
	v_mfma_f32_16x16x32_bf16 v[28:31], v[128:131], v[218:221], v[28:31]
	v_mfma_f32_16x16x32_bf16 v[24:27], v[152:155], v[218:221], v[24:27]
	v_mfma_f32_16x16x32_bf16 v[12:15], v[128:131], v[226:229], v[12:15]
	v_mfma_f32_16x16x32_bf16 v[8:11], v[152:155], v[226:229], v[8:11]
	v_mfma_f32_16x16x32_bf16 v[60:63], v[132:135], v[206:209], v[60:63]
	v_mfma_f32_16x16x32_bf16 v[56:59], v[156:159], v[206:209], v[56:59]
	v_mfma_f32_16x16x32_bf16 v[44:47], v[132:135], v[214:217], v[44:47]
	v_mfma_f32_16x16x32_bf16 v[40:43], v[156:159], v[214:217], v[40:43]
	v_mfma_f32_16x16x32_bf16 v[28:31], v[132:135], v[222:225], v[28:31]
	v_mfma_f32_16x16x32_bf16 v[24:27], v[156:159], v[222:225], v[24:27]
	v_mfma_f32_16x16x32_bf16 v[12:15], v[132:135], v[230:233], v[12:15]
	v_mfma_f32_16x16x32_bf16 v[8:11], v[156:159], v[230:233], v[8:11]
	s_setprio 0
	s_setprio 1
	v_mfma_f32_16x16x32_bf16 v[52:55], v[160:163], v[202:205], v[52:55]
	v_mfma_f32_16x16x32_bf16 v[48:51], v[194:197], v[202:205], v[48:51]
	v_mfma_f32_16x16x32_bf16 v[36:39], v[160:163], v[210:213], v[36:39]
	v_mfma_f32_16x16x32_bf16 v[32:35], v[194:197], v[210:213], v[32:35]
	v_mfma_f32_16x16x32_bf16 v[20:23], v[160:163], v[218:221], v[20:23]
	v_mfma_f32_16x16x32_bf16 v[16:19], v[194:197], v[218:221], v[16:19]
	v_mfma_f32_16x16x32_bf16 v[4:7], v[160:163], v[226:229], v[4:7]
	v_mfma_f32_16x16x32_bf16 v[0:3], v[194:197], v[226:229], v[0:3]
	v_mfma_f32_16x16x32_bf16 v[52:55], v[170:173], v[206:209], v[52:55]
	v_mfma_f32_16x16x32_bf16 v[48:51], v[198:201], v[206:209], v[48:51]
	v_mfma_f32_16x16x32_bf16 v[36:39], v[170:173], v[214:217], v[36:39]
	v_mfma_f32_16x16x32_bf16 v[32:35], v[198:201], v[214:217], v[32:35]
	v_mfma_f32_16x16x32_bf16 v[20:23], v[170:173], v[222:225], v[20:23]
	v_mfma_f32_16x16x32_bf16 v[16:19], v[198:201], v[222:225], v[16:19]
	v_mfma_f32_16x16x32_bf16 v[4:7], v[170:173], v[230:233], v[4:7]
	v_mfma_f32_16x16x32_bf16 v[0:3], v[198:201], v[230:233], v[0:3]
	s_setprio 0
	s_barrier
	s_add_i32 s68, 0, 0x18000
	v_add_u32_e32 v136, s68, v168
	s_add_i32 s69, 0, 0x1c000
	ds_read_b128 v[128:131], v136
	ds_read_b128 v[132:135], v136 offset:1024
	ds_read_b128 v[152:155], v136 offset:2048
	ds_read_b128 v[156:159], v136 offset:3072
	v_add_u32_e32 v136, s69, v168
	ds_read_b128 v[160:163], v136
	ds_read_b128 v[170:173], v136 offset:1024
	ds_read_b128 v[194:197], v136 offset:2048
	ds_read_b128 v[198:201], v136 offset:3072
	s_add_u32 s100, s8, 0x40000
	s_addc_u32 s101, s9, 0
	s_mov_b32 m0, s50
	ds_read_b128 v[202:205], v169 offset:32768
	ds_read_b128 v[206:209], v169 offset:33792
	ds_read_b128 v[210:213], v169 offset:34816
	ds_read_b128 v[214:217], v169 offset:35840
	ds_read_b128 v[218:221], v169 offset:36864
	ds_read_b128 v[222:225], v169 offset:37888
	ds_read_b128 v[226:229], v169 offset:38912
	ds_read_b128 v[230:233], v169 offset:39936
	global_load_lds_dwordx4 v146, s[100:101]
	s_mov_b32 m0, s51
	s_nop 0
	global_load_lds_dwordx4 v142, s[100:101]
	s_waitcnt vmcnt(8)
	s_waitcnt lgkmcnt(0)
	s_barrier
	s_setprio 1
	s_waitcnt lgkmcnt(0)
	v_mfma_f32_16x16x32_bf16 v[124:127], v[128:131], v[202:205], v[124:127]
	v_mfma_f32_16x16x32_bf16 v[120:123], v[152:155], v[202:205], v[120:123]
	v_mfma_f32_16x16x32_bf16 v[108:111], v[128:131], v[210:213], v[108:111]
	v_mfma_f32_16x16x32_bf16 v[104:107], v[152:155], v[210:213], v[104:107]
	v_mfma_f32_16x16x32_bf16 v[92:95], v[128:131], v[218:221], v[92:95]
	v_mfma_f32_16x16x32_bf16 v[88:91], v[152:155], v[218:221], v[88:91]
	v_mfma_f32_16x16x32_bf16 v[76:79], v[128:131], v[226:229], v[76:79]
	v_mfma_f32_16x16x32_bf16 v[72:75], v[152:155], v[226:229], v[72:75]
	v_mfma_f32_16x16x32_bf16 v[124:127], v[132:135], v[206:209], v[124:127]
	v_mfma_f32_16x16x32_bf16 v[120:123], v[156:159], v[206:209], v[120:123]
	v_mfma_f32_16x16x32_bf16 v[108:111], v[132:135], v[214:217], v[108:111]
	v_mfma_f32_16x16x32_bf16 v[104:107], v[156:159], v[214:217], v[104:107]
	v_mfma_f32_16x16x32_bf16 v[92:95], v[132:135], v[222:225], v[92:95]
	v_mfma_f32_16x16x32_bf16 v[88:91], v[156:159], v[222:225], v[88:91]
	v_mfma_f32_16x16x32_bf16 v[76:79], v[132:135], v[230:233], v[76:79]
	v_mfma_f32_16x16x32_bf16 v[72:75], v[156:159], v[230:233], v[72:75]
	s_setprio 0
	s_setprio 1
	v_mfma_f32_16x16x32_bf16 v[116:119], v[160:163], v[202:205], v[116:119]
	v_mfma_f32_16x16x32_bf16 v[112:115], v[194:197], v[202:205], v[112:115]
	v_mfma_f32_16x16x32_bf16 v[100:103], v[160:163], v[210:213], v[100:103]
	v_mfma_f32_16x16x32_bf16 v[96:99], v[194:197], v[210:213], v[96:99]
	v_mfma_f32_16x16x32_bf16 v[84:87], v[160:163], v[218:221], v[84:87]
	v_mfma_f32_16x16x32_bf16 v[80:83], v[194:197], v[218:221], v[80:83]
	v_mfma_f32_16x16x32_bf16 v[68:71], v[160:163], v[226:229], v[68:71]
	v_mfma_f32_16x16x32_bf16 v[64:67], v[194:197], v[226:229], v[64:67]
	v_mfma_f32_16x16x32_bf16 v[116:119], v[170:173], v[206:209], v[116:119]
	v_mfma_f32_16x16x32_bf16 v[112:115], v[198:201], v[206:209], v[112:115]
	v_mfma_f32_16x16x32_bf16 v[100:103], v[170:173], v[214:217], v[100:103]
	v_mfma_f32_16x16x32_bf16 v[96:99], v[198:201], v[214:217], v[96:99]
	v_mfma_f32_16x16x32_bf16 v[84:87], v[170:173], v[222:225], v[84:87]
	v_mfma_f32_16x16x32_bf16 v[80:83], v[198:201], v[222:225], v[80:83]
	v_mfma_f32_16x16x32_bf16 v[68:71], v[170:173], v[230:233], v[68:71]
	v_mfma_f32_16x16x32_bf16 v[64:67], v[198:201], v[230:233], v[64:67]
	s_setprio 0
	s_barrier
	s_add_i32 s100, s68, s47
	s_add_u32 s6, s6, 0x80
	s_addc_u32 s7, s7, 0
	s_mov_b32 m0, s100
	ds_read_b128 v[202:205], v169 offset:49152
	ds_read_b128 v[206:209], v169 offset:50176
	ds_read_b128 v[210:213], v169 offset:51200
	ds_read_b128 v[214:217], v169 offset:52224
	ds_read_b128 v[218:221], v169 offset:53248
	ds_read_b128 v[222:225], v169 offset:54272
	ds_read_b128 v[226:229], v169 offset:55296
	ds_read_b128 v[230:233], v169 offset:56320
	global_load_lds_dwordx4 v144, s[6:7]
	s_add_i32 m0, s100, 0x2000
	s_add_i32 s100, s69, s47
	global_load_lds_dwordx4 v140, s[6:7]
	s_add_u32 s6, s6, 0x40000
	s_addc_u32 s7, s7, 0
	s_mov_b32 m0, s100
	s_nop 0
	global_load_lds_dwordx4 v144, s[6:7]
	s_add_i32 m0, s100, 0x2000
	s_add_u32 s8, s8, 0x80
	s_addc_u32 s9, s9, 0
	s_nop 0
	global_load_lds_dwordx4 v140, s[6:7]
	s_mov_b32 m0, s54
	s_nop 0
	global_load_lds_dwordx4 v146, s[8:9]
	s_mov_b32 m0, s55
	s_nop 0
	global_load_lds_dwordx4 v142, s[8:9]
	s_waitcnt vmcnt(8)
	s_waitcnt lgkmcnt(0)
	s_barrier
	s_setprio 1
	s_waitcnt lgkmcnt(0)
	v_mfma_f32_16x16x32_bf16 v[60:63], v[128:131], v[202:205], v[60:63]
	v_mfma_f32_16x16x32_bf16 v[56:59], v[152:155], v[202:205], v[56:59]
	v_mfma_f32_16x16x32_bf16 v[44:47], v[128:131], v[210:213], v[44:47]
	v_mfma_f32_16x16x32_bf16 v[40:43], v[152:155], v[210:213], v[40:43]
	v_mfma_f32_16x16x32_bf16 v[28:31], v[128:131], v[218:221], v[28:31]
	v_mfma_f32_16x16x32_bf16 v[24:27], v[152:155], v[218:221], v[24:27]
	v_mfma_f32_16x16x32_bf16 v[12:15], v[128:131], v[226:229], v[12:15]
	v_mfma_f32_16x16x32_bf16 v[8:11], v[152:155], v[226:229], v[8:11]
	v_mfma_f32_16x16x32_bf16 v[60:63], v[132:135], v[206:209], v[60:63]
	v_mfma_f32_16x16x32_bf16 v[56:59], v[156:159], v[206:209], v[56:59]
	v_mfma_f32_16x16x32_bf16 v[44:47], v[132:135], v[214:217], v[44:47]
	v_mfma_f32_16x16x32_bf16 v[40:43], v[156:159], v[214:217], v[40:43]
	v_mfma_f32_16x16x32_bf16 v[28:31], v[132:135], v[222:225], v[28:31]
	v_mfma_f32_16x16x32_bf16 v[24:27], v[156:159], v[222:225], v[24:27]
	v_mfma_f32_16x16x32_bf16 v[12:15], v[132:135], v[230:233], v[12:15]
	v_mfma_f32_16x16x32_bf16 v[8:11], v[156:159], v[230:233], v[8:11]
	s_setprio 0
	s_setprio 1
	v_mfma_f32_16x16x32_bf16 v[52:55], v[160:163], v[202:205], v[52:55]
	v_mfma_f32_16x16x32_bf16 v[48:51], v[194:197], v[202:205], v[48:51]
	v_mfma_f32_16x16x32_bf16 v[36:39], v[160:163], v[210:213], v[36:39]
	v_mfma_f32_16x16x32_bf16 v[32:35], v[194:197], v[210:213], v[32:35]
	v_mfma_f32_16x16x32_bf16 v[20:23], v[160:163], v[218:221], v[20:23]
	v_mfma_f32_16x16x32_bf16 v[16:19], v[194:197], v[218:221], v[16:19]
	v_mfma_f32_16x16x32_bf16 v[4:7], v[160:163], v[226:229], v[4:7]
	v_mfma_f32_16x16x32_bf16 v[0:3], v[194:197], v[226:229], v[0:3]
	v_mfma_f32_16x16x32_bf16 v[52:55], v[170:173], v[206:209], v[52:55]
	v_mfma_f32_16x16x32_bf16 v[48:51], v[198:201], v[206:209], v[48:51]
	v_mfma_f32_16x16x32_bf16 v[36:39], v[170:173], v[214:217], v[36:39]
	v_mfma_f32_16x16x32_bf16 v[32:35], v[198:201], v[214:217], v[32:35]
	v_mfma_f32_16x16x32_bf16 v[20:23], v[170:173], v[222:225], v[20:23]
	v_mfma_f32_16x16x32_bf16 v[16:19], v[198:201], v[222:225], v[16:19]
	v_mfma_f32_16x16x32_bf16 v[4:7], v[170:173], v[230:233], v[4:7]
	v_mfma_f32_16x16x32_bf16 v[0:3], v[198:201], v[230:233], v[0:3]
	s_setprio 0
	s_barrier
	s_add_i32 s67, s67, 2
	s_add_u32 s2, s2, 0x100
	s_addc_u32 s3, s3, 0
	s_add_u32 s65, s65, 0x100
	s_addc_u32 s66, s66, 0
	s_cmp_gt_u32 s67, 13
	s_cbranch_scc0 .LBB0_233
	s_and_b64 vcc, exec, s[12:13]
	s_cbranch_vccz .LBB0_236
	s_barrier

	.amdhsa_kernel _ZN2mk6mk_fwdENS_4ArgsE
		.amdhsa_group_segment_fixed_size 0
		.amdhsa_private_segment_fixed_size 0
		.amdhsa_kernarg_size 512
		.amdhsa_user_sgpr_count 2
		.amdhsa_user_sgpr_dispatch_ptr 0
		.amdhsa_user_sgpr_queue_ptr 0
		.amdhsa_user_sgpr_kernarg_segment_ptr 1
		.amdhsa_user_sgpr_dispatch_id 0
		.amdhsa_user_sgpr_kernarg_preload_length 0
		.amdhsa_user_sgpr_kernarg_preload_offset 0
		.amdhsa_user_sgpr_private_segment_size 0
		.amdhsa_uses_dynamic_stack 0
		.amdhsa_enable_private_segment 0
		.amdhsa_system_sgpr_workgroup_id_x 1
		.amdhsa_system_sgpr_workgroup_id_y 0
		.amdhsa_system_sgpr_workgroup_id_z 0
		.amdhsa_system_sgpr_workgroup_info 0
		.amdhsa_system_vgpr_workitem_id 0
		.amdhsa_next_free_vgpr 256
		.amdhsa_next_free_sgpr 102
		.amdhsa_accum_offset 256
		.amdhsa_reserve_vcc 1
		.amdhsa_float_round_mode_32 0
		.amdhsa_float_round_mode_16_64 0
		.amdhsa_float_denorm_mode_32 3
		.amdhsa_float_denorm_mode_16_64 3
		.amdhsa_dx10_clamp 1
		.amdhsa_ieee_mode 1
		.amdhsa_fp16_overflow 0
		.amdhsa_tg_split 0
		.amdhsa_exception_fp_ieee_invalid_op 0
		.amdhsa_exception_fp_denorm_src 0
		.amdhsa_exception_fp_ieee_div_zero 0
		.amdhsa_exception_fp_ieee_overflow 0
		.amdhsa_exception_fp_ieee_underflow 0
		.amdhsa_exception_fp_ieee_inexact 0
		.amdhsa_exception_int_div_zero 0
	.end_amdhsa_kernel

amdhsa.kernels:
  - .agpr_count:     0
    .args:
      - .offset:         0
        .size:           256
        .value_kind:     by_value
      - .offset:         256
        .size:           4
        .value_kind:     hidden_block_count_x
      - .offset:         260
        .size:           4
        .value_kind:     hidden_block_count_y
      - .offset:         264
        .size:           4
        .value_kind:     hidden_block_count_z
      - .offset:         268
        .size:           2
        .value_kind:     hidden_group_size_x
      - .offset:         270
        .size:           2
        .value_kind:     hidden_group_size_y
      - .offset:         272
        .size:           2
        .value_kind:     hidden_group_size_z
      - .offset:         274
        .size:           2
        .value_kind:     hidden_remainder_x
      - .offset:         276
        .size:           2
        .value_kind:     hidden_remainder_y
      - .offset:         278
        .size:           2
        .value_kind:     hidden_remainder_z
      - .offset:         296
        .size:           8
        .value_kind:     hidden_global_offset_x
      - .offset:         304
        .size:           8
        .value_kind:     hidden_global_offset_y
      - .offset:         312
        .size:           8
        .value_kind:     hidden_global_offset_z
      - .offset:         320
        .size:           2
        .value_kind:     hidden_grid_dims
      - .offset:         376
        .size:           4
        .value_kind:     hidden_dynamic_lds_size
    .group_segment_fixed_size: 0
    .kernarg_segment_align: 8
    .kernarg_segment_size: 512
    .language:       OpenCL C
    .language_version:
      - 2
      - 0
    .max_flat_workgroup_size: 512
    .name:           _ZN2mk6mk_fwdENS_4ArgsE
    .private_segment_fixed_size: 0
    .sgpr_count:     108
    .sgpr_spill_count: 202
    .symbol:         _ZN2mk6mk_fwdENS_4ArgsE.kd
    .uniform_work_group_size: 1
    .uses_dynamic_stack: false
    .vgpr_count:     256
    .vgpr_spill_count: 0
    .wavefront_size: 64
